# A/B of the static priority raise: waves 0-3 instead of 4-7 (attention phases), on top of v37
# baseline (speedup 1.0000x reference)
; __global__ void __launch_bounds__(512, 2) mega(Params p) {
;     ...
;     for (int rp = 0; rp < REP_P2; ++rp)
;     for (int item = bid; item < 512; item += nb) {
;       const int idx = item & 255;
;       const int pl = idx & 7, rest = idx >> 3;
;       AttArgs a{};
;       int Lp2 = L; asm volatile("" : "+s"(Lp2));
.LBB0_631:
	v_readfirstlane_b32 s100, v224
	s_nop 0
	s_cmpk_ge_u32 s100, 0x100
	s_cbranch_scc1 .Lprio_p2
	s_setprio 1

; #define GSYNC() do { for (int _r = 0; _r < REP_SYNC; ++_r) xcd_barrier(xbar); } while (0)
; __global__ void __launch_bounds__(512, 2) mega(Params p) {
;     ...
;     GSYNC();
;     for (int rp = 0; rp < REP_P4; ++rp)
;     for (int item = bid; item < 256; item += nb) {
.LBB0_1072:
	s_or_b64 exec, exec, s[0:1]
	v_readlane_b32 s0, v253, 38
	v_readlane_b32 s1, v253, 39
	s_andn2_b64 vcc, exec, s[0:1]
	v_readlane_b32 s14, v252, 0
	s_waitcnt lgkmcnt(0)
	s_barrier
	v_readfirstlane_b32 s100, v224
	s_nop 0
	s_cmpk_ge_u32 s100, 0x100
	s_cbranch_scc1 .Lprio_p5
	s_setprio 1
